# ACQ-HOIST2: the XCD leaders that wait for the cross-XCD release also issue their acquire invalidate when they start waiting (on ACQ-HOIST)
# baseline (speedup 1.0000x reference)
.LBB0_74:
	s_andn2_saveexec_b64 s[0:1], s[10:11]
	s_cbranch_execz .LBB0_94
	s_mov_b64 s[10:11], exec
	s_mov_b32 s97, 0
	buffer_wbl2 sc1
	s_waitcnt lgkmcnt(0)
	s_waitcnt vmcnt(0)
	v_mbcnt_lo_u32_b32 v2, s10, 0
	v_mbcnt_hi_u32_b32 v2, s11, v2
	v_cmp_eq_u32_e32 vcc, 0, v2
	s_and_saveexec_b64 s[12:13], vcc
	s_cbranch_execz .LBB0_77
	s_bcnt1_i32_b64 s0, s[10:11]
	v_mov_b32_e32 v4, s0
	v_readlane_b32 s0, v255, 5
	v_mov_b32_e32 v3, 0x4000
	v_readlane_b32 s1, v255, 6
	s_nop 4
	global_atomic_add v3, v3, v4, s[0:1] offset:1024 sc0
.LBB0_77:
	s_or_b64 exec, exec, s[12:13]
	v_cvt_f32_u32_e32 v4, v1
	s_waitcnt vmcnt(0)
	v_readfirstlane_b32 s0, v3
	s_mov_b64 s[14:15], -1
	v_rcp_iflag_f32_e32 v4, v4
	v_add_u32_e32 v2, s0, v2
	v_add_u32_e32 v5, 1, v2
	v_readlane_b32 s0, v255, 5
	v_mul_f32_e32 v3, 0x4f7ffffe, v4
	v_cvt_u32_f32_e32 v3, v3
	v_sub_u32_e32 v4, 0, v1
	v_readlane_b32 s1, v255, 6
	s_add_u32 s12, s0, 0x4500
	v_mul_lo_u32 v4, v4, v3
	v_mul_hi_u32 v4, v3, v4
	v_add_u32_e32 v3, v3, v4
	v_mul_hi_u32 v3, v2, v3
	v_mul_lo_u32 v4, v3, v1
	v_sub_u32_e32 v2, v2, v4
	v_add_u32_e32 v6, 1, v3
	v_cmp_ge_u32_e32 vcc, v2, v1
	v_sub_u32_e32 v4, v2, v1
	s_addc_u32 s13, s1, 0
	v_cndmask_b32_e32 v3, v3, v6, vcc
	v_cndmask_b32_e32 v2, v2, v4, vcc
	v_add_u32_e32 v4, 1, v3
	v_cmp_ge_u32_e32 vcc, v2, v1
	s_nop 1
	v_cndmask_b32_e32 v4, v3, v4, vcc
	v_mul_lo_u32 v2, v1, v4
	v_add_u32_e32 v1, v2, v1
	v_cmp_ne_u32_e32 vcc, v5, v1
	v_mov_b64_e32 v[2:3], s[12:13]
	s_and_saveexec_b64 s[10:11], vcc
	s_cbranch_execz .LBB0_89
	s_mov_b32 s97, 1
	buffer_inv sc1
	v_mov_b32_e32 v1, 0
	global_load_dword v2, v1, s[12:13] sc1
	s_mov_b64 s[18:19], 0
	s_waitcnt vmcnt(0)
	v_cmp_eq_u32_e32 vcc, v2, v4
	s_and_saveexec_b64 s[16:17], vcc
	s_cbranch_execz .LBB0_88
	v_readlane_b32 s0, v255, 5
	v_readlane_b32 s1, v255, 6
	s_add_u32 s14, s0, 0x1200
	s_addc_u32 s15, s1, 0
	s_mov_b32 s0, 1
	s_branch .LBB0_81

.LBB0_91:
	s_or_b64 exec, exec, s[10:11]
	s_mov_b64 s[10:11], exec
	v_mbcnt_lo_u32_b32 v1, s10, 0
	v_mbcnt_hi_u32_b32 v1, s11, v1
	v_cmp_eq_u32_e32 vcc, 0, v1
	s_waitcnt vmcnt(0)
	s_cmp_eq_u32 s97, 1
	s_cbranch_scc1 .Lacq2_skip_11
	buffer_inv sc1
.Lacq2_skip_11:
	s_and_saveexec_b64 s[12:13], vcc
	s_cbranch_execz .LBB0_93
	s_bcnt1_i32_b64 s0, s[10:11]
	v_mov_b32_e32 v1, 0x2000
	v_mov_b32_e32 v2, s0
	global_atomic_add v1, v2, s[8:9] offset:1024
